# removed stray vmcnt(0) in EpiRes K-loop + EpiRes prologue batched + exact vmcnt + sw_rows grouped prefetch + silu batched + QKV V^T prologue batched
# speedup vs baseline: 1.0164x; 1.0119x over previous
.LBB0_5:
	s_or_b64 exec, exec, s[2:3]
	s_cmp_ge_i32 s24, s25
	s_cbranch_scc0 .Lentry_go
	s_endpgm
.Lentry_go:
	s_load_dwordx8 s[8:15], s[0:1], 0xc0
	s_lshr_b32 s2, s7, 6
	v_writelane_b32 v252, s2, 13
	s_add_u32 s2, s0, 0xf8
	s_addc_u32 s3, s1, 0
	s_load_dwordx16 s[36:51], s[0:1], 0x0
	s_load_dwordx16 s[52:67], s[0:1], 0x40
	v_writelane_b32 v252, s2, 14
	s_load_dwordx2 s[4:5], s[0:1], 0xe0
	s_load_dwordx16 s[72:87], s[0:1], 0x80
	v_writelane_b32 v252, s3, 15
	s_waitcnt lgkmcnt(0)
	s_add_u32 s2, s14, 0x4000000
	s_addc_u32 s3, s15, 0
	v_writelane_b32 v252, s2, 16
	v_mov_b32_e32 v1, 0
	v_mov_b32_e32 v202, 0x358637bd
	v_writelane_b32 v252, s3, 17
	s_add_u32 s2, s38, 0xfe000000
	v_writelane_b32 v252, s2, 18
	s_addc_u32 s2, s39, -1
	v_writelane_b32 v252, s2, 19
	s_add_u32 s2, s58, 0x1600000
	v_writelane_b32 v252, s2, 20
	s_addc_u32 s2, s59, 0
	s_cmp_eq_u32 s6, 15
	v_writelane_b32 v252, s2, 21
	s_cselect_b64 s[2:3], -1, 0
	v_writelane_b32 v252, s2, 22
	s_cmp_eq_u32 s6, 14
	v_mov_b32_e32 v203, 1
	v_writelane_b32 v252, s3, 23
	s_cselect_b64 s[2:3], -1, 0
	v_writelane_b32 v252, s2, 24
	s_cmp_eq_u32 s6, 13
	v_mov_b32_e32 v204, 0x9000
	v_writelane_b32 v252, s3, 25
	s_cselect_b64 s[2:3], -1, 0
	v_writelane_b32 v252, s2, 26
	s_cmp_eq_u32 s6, 12
	v_mov_b64_e32 v[210:211], 0xc0
	v_writelane_b32 v252, s3, 27
	s_cselect_b64 s[2:3], -1, 0
	v_writelane_b32 v252, s2, 28
	s_cmp_eq_u32 s6, 11
	v_mov_b64_e32 v[212:213], 0xbf
	v_writelane_b32 v252, s3, 29
	s_cselect_b64 s[2:3], -1, 0
	v_writelane_b32 v252, s2, 30
	s_cmp_eq_u32 s6, 10
	s_mov_b32 s93, 0x1b000
	v_writelane_b32 v252, s3, 31
	s_cselect_b64 s[2:3], -1, 0
	v_writelane_b32 v252, s2, 32
	s_cmp_eq_u32 s6, 9
	s_mov_b32 s70, 0x9000
	v_writelane_b32 v252, s3, 33
	s_cselect_b64 s[2:3], -1, 0
	v_writelane_b32 v252, s2, 34
	s_cmp_eq_u32 s6, 8
	s_mov_b32 s71, 0x12000
	v_writelane_b32 v252, s3, 35
	s_cselect_b64 s[2:3], -1, 0
	v_writelane_b32 v252, s2, 36
	s_cmp_eq_u32 s6, 7
	s_mov_b32 s68, 0x800000
	v_writelane_b32 v252, s3, 37
	s_cselect_b64 s[2:3], -1, 0
	v_writelane_b32 v252, s2, 38
	s_cmp_eq_u32 s6, 6
	s_movk_i32 s69, 0xfe00
	v_writelane_b32 v252, s3, 39
	s_cselect_b64 s[2:3], -1, 0
	v_writelane_b32 v252, s2, 40
	s_cmp_eq_u32 s6, 5
	s_mov_b32 s92, 0x48000
	v_writelane_b32 v252, s3, 41
	s_cselect_b64 s[2:3], -1, 0
	v_writelane_b32 v252, s2, 42
	s_cmp_eq_u32 s6, 4
	s_mov_b32 s33, 0x24000
	v_writelane_b32 v252, s3, 43
	s_cselect_b64 s[2:3], -1, 0
	v_writelane_b32 v252, s2, 44
	s_cmp_eq_u32 s6, 3
	s_mov_b32 s34, 0x2d000
	v_writelane_b32 v252, s3, 45
	s_cselect_b64 s[2:3], -1, 0
	v_writelane_b32 v252, s2, 46
	s_cmp_eq_u32 s6, 2
	s_mov_b32 s35, 0x36000
	v_writelane_b32 v252, s3, 47
	s_cselect_b64 s[2:3], -1, 0
	v_writelane_b32 v252, s2, 48
	s_cmp_eq_u32 s6, 1
	s_mov_b32 s20, 0x3f000
	v_writelane_b32 v252, s3, 49
	s_cselect_b64 s[2:3], -1, 0
	v_writelane_b32 v252, s2, 50
	s_cmp_eq_u32 s6, 0
	s_mov_b32 s16, 0x63000
	v_writelane_b32 v252, s3, 51
	s_cselect_b64 s[2:3], -1, 0
	v_writelane_b32 v252, s2, 52
	s_mov_b32 s88, 0x7e000
	s_mov_b32 s89, 0xc6000
	v_writelane_b32 v252, s3, 53
	s_lshl_b32 s2, s6, 6
	s_add_u32 s3, s4, 0x20000
	v_writelane_b32 v252, s3, 54
	s_addc_u32 s3, s5, 0
	v_writelane_b32 v252, s3, 55
	s_add_u32 s3, s4, 0x6000400
	v_writelane_b32 v252, s3, 56
	s_addc_u32 s3, s5, 0
	v_writelane_b32 v252, s3, 57
	s_add_u32 s3, s4, 0x200000
	v_writelane_b32 v252, s3, 58
	s_addc_u32 s3, s5, 0
	v_writelane_b32 v252, s3, 59
	s_add_u32 s3, s4, 0x400000
	v_writelane_b32 v252, s3, 60
	s_addc_u32 s3, s5, 0
	v_writelane_b32 v252, s3, 61
	s_add_u32 s3, s4, 0x4d20000
	v_writelane_b32 v252, s3, 62
	s_addc_u32 s3, s5, 0
	v_writelane_b32 v252, s3, 63
	s_add_u32 s3, s4, 0x7040080
	v_writelane_b32 v253, s3, 0
	s_addc_u32 s3, s5, 0
	v_writelane_b32 v253, s3, 1
	s_add_u32 s3, s4, 0x1200100
	v_writelane_b32 v253, s3, 2
	s_addc_u32 s3, s5, 0
	v_writelane_b32 v253, s3, 3
	s_add_u32 s3, s4, 0x3980000
	v_writelane_b32 v253, s3, 4
	s_addc_u32 s3, s5, 0
	v_writelane_b32 v253, s3, 5
	s_add_u32 s3, s4, 0x5100000
	v_writelane_b32 v253, s3, 6
	s_addc_u32 s3, s5, 0
	v_writelane_b32 v253, s3, 7
	s_add_u32 s3, s4, 0x2900000
	v_writelane_b32 v253, s3, 8
	s_addc_u32 s3, s5, 0
	v_writelane_b32 v253, s3, 9
	s_add_u32 s3, s4, 0x1880000
	v_writelane_b32 v253, s3, 10
	s_addc_u32 s3, s5, 0
	v_writelane_b32 v253, s3, 11
	s_lshl_b32 s2, s2, 2
	v_writelane_b32 v253, s2, 12
	s_add_i32 s2, 0, 0x11000
	v_writelane_b32 v253, s2, 13
	s_add_i32 s2, 0, 0x8fc0
	v_writelane_b32 v253, s2, 14
	s_add_i32 s2, 0, 0x20fc0
	v_writelane_b32 v253, s2, 15
	s_add_i32 s2, 0, 0x20fc4
	v_writelane_b32 v253, s2, 16
	v_writelane_b32 v253, s72, 17
	s_mov_b32 s90, 0xe1000
	s_mov_b32 s31, 0
	v_writelane_b32 v253, s73, 18
	v_writelane_b32 v253, s74, 19
	v_writelane_b32 v253, s75, 20
	v_writelane_b32 v253, s76, 21
	v_writelane_b32 v253, s77, 22
	v_writelane_b32 v253, s78, 23
	v_writelane_b32 v253, s79, 24
	v_writelane_b32 v253, s80, 25
	v_writelane_b32 v253, s81, 26
	v_writelane_b32 v253, s82, 27
	v_writelane_b32 v253, s83, 28
	v_writelane_b32 v253, s84, 29
	v_writelane_b32 v253, s85, 30
	v_writelane_b32 v253, s86, 31
	v_writelane_b32 v253, s87, 32
	v_writelane_b32 v253, s36, 33
	s_mov_b64 s[96:97], 0x80
	s_nop 0
	v_writelane_b32 v253, s37, 34
	v_writelane_b32 v253, s38, 35
	v_writelane_b32 v253, s39, 36
	v_writelane_b32 v253, s40, 37
	v_writelane_b32 v253, s41, 38
	v_writelane_b32 v253, s42, 39
	v_writelane_b32 v253, s43, 40
	v_writelane_b32 v253, s44, 41
	v_writelane_b32 v253, s45, 42
	v_writelane_b32 v253, s46, 43
	v_writelane_b32 v253, s47, 44
	v_writelane_b32 v253, s48, 45
	v_writelane_b32 v253, s49, 46
	v_writelane_b32 v253, s50, 47
	v_writelane_b32 v253, s51, 48
	v_writelane_b32 v253, s52, 49
	s_nop 1
	v_writelane_b32 v253, s53, 50
	v_writelane_b32 v253, s54, 51
	v_writelane_b32 v253, s55, 52
	v_writelane_b32 v253, s56, 53
	v_writelane_b32 v253, s57, 54
	v_writelane_b32 v253, s58, 55
	v_writelane_b32 v253, s59, 56
	v_writelane_b32 v253, s60, 57
	v_writelane_b32 v253, s61, 58
	v_writelane_b32 v253, s62, 59
	v_writelane_b32 v253, s63, 60
	v_writelane_b32 v253, s64, 61
	v_writelane_b32 v253, s65, 62
	v_writelane_b32 v253, s66, 63
	v_writelane_b32 v254, s67, 0
	s_branch .LBB0_9

.LBB0_8:
	s_mov_b32 s24, s2
	s_cmp_ge_i32 s2, s25
	s_cbranch_scc0 .LBB0_9
	s_endpgm

.LBB0_150:
	v_cmp_ne_u32_e32 vcc, 0, v0
	v_mov_b32_e32 v216, v199
	v_mov_b32_e32 v215, v198
	s_cbranch_vccz .LBB0_344
	s_sub_i32 s0, s12, 32
	s_lshr_b32 s0, s0, 3
	s_lshl_b32 s4, s12, 8
	s_mul_i32 s2, s0, 0xa00
	s_ashr_i32 s5, s4, 31
	s_addk_i32 s2, 0x1100
	s_lshl_b64 s[0:1], s[4:5], 2
	s_add_u32 s0, s69, s0
	v_lshlrev_b32_e32 v150, 2, v216
	s_addc_u32 s1, s70, s1
	v_ashrrev_i32_e32 v151, 31, v150
	v_lshl_add_u64 v[146:147], v[150:151], 2, s[0:1]
	global_load_dwordx4 v[130:133], v[146:147], off
	global_load_dwordx4 v[186:189], v[146:147], off offset:64
	global_load_dwordx4 v[190:193], v[146:147], off offset:512
	global_load_dwordx4 v[194:197], v[146:147], off offset:576
	s_mov_b32 s0, 0x358637bd
	v_mov_b64_e32 v[148:149], s[0:1]
	s_mov_b32 s6, 0x3a800000
	s_mov_b32 s3, 0x800000
	s_mov_b32 s8, 0x45800000
	s_cmp_lt_i32 s12, 32
	s_waitcnt vmcnt(3)
	v_pk_fma_f32 v[130:131], v[130:131], s[6:7], v[148:149] op_sel_hi:[1,0,0]
	s_nop 0
	v_mul_f32_e32 v0, 0x4b800000, v130
	v_cmp_gt_f32_e64 s[0:1], s3, v130
	v_cmp_gt_f32_e32 vcc, s3, v131
	s_nop 0
	v_cndmask_b32_e64 v0, v130, v0, s[0:1]
	v_rsq_f32_e32 v130, v0
	v_mul_f32_e32 v0, 0x4b800000, v131
	v_cndmask_b32_e32 v0, v131, v0, vcc
	v_rsq_f32_e32 v131, v0
	s_nop 0
	v_pk_mul_f32 v[134:135], v[130:131], s[8:9] op_sel_hi:[1,0]
	s_nop 0
	v_cndmask_b32_e32 v143, v131, v135, vcc
	v_cndmask_b32_e64 v142, v130, v134, s[0:1]
	v_pk_fma_f32 v[130:131], v[132:133], s[6:7], v[148:149] op_sel_hi:[1,0,0]
	s_nop 0
	v_mul_f32_e32 v0, 0x4b800000, v130
	v_cmp_gt_f32_e64 s[0:1], s3, v130
	v_cmp_gt_f32_e32 vcc, s3, v131
	s_nop 0
	v_cndmask_b32_e64 v0, v130, v0, s[0:1]
	v_rsq_f32_e32 v130, v0
	v_mul_f32_e32 v0, 0x4b800000, v131
	v_cndmask_b32_e32 v0, v131, v0, vcc
	v_rsq_f32_e32 v131, v0
	s_nop 0
	v_pk_mul_f32 v[132:133], v[130:131], s[8:9] op_sel_hi:[1,0]
	s_nop 0
	v_cndmask_b32_e32 v145, v131, v133, vcc
	v_cndmask_b32_e64 v144, v130, v132, s[0:1]
	s_waitcnt vmcnt(2)
	v_mov_b32_e32 v130, v186
	v_mov_b32_e32 v131, v187
	v_mov_b32_e32 v132, v188
	v_mov_b32_e32 v133, v189
	v_pk_fma_f32 v[130:131], v[130:131], s[6:7], v[148:149] op_sel_hi:[1,0,0]
	s_nop 0
	v_mul_f32_e32 v0, 0x4b800000, v130
	v_cmp_gt_f32_e64 s[0:1], s3, v130
	v_cmp_gt_f32_e32 vcc, s3, v131
	s_nop 0
	v_cndmask_b32_e64 v0, v130, v0, s[0:1]
	v_rsq_f32_e32 v130, v0
	v_mul_f32_e32 v0, 0x4b800000, v131
	v_cndmask_b32_e32 v0, v131, v0, vcc
	v_rsq_f32_e32 v131, v0
	s_nop 0
	v_pk_mul_f32 v[134:135], v[130:131], s[8:9] op_sel_hi:[1,0]
	s_nop 0
	v_cndmask_b32_e32 v139, v131, v135, vcc
	v_cndmask_b32_e64 v138, v130, v134, s[0:1]
	v_pk_fma_f32 v[130:131], v[132:133], s[6:7], v[148:149] op_sel_hi:[1,0,0]
	s_nop 0
	v_mul_f32_e32 v0, 0x4b800000, v130
	v_cmp_gt_f32_e64 s[0:1], s3, v130
	v_cmp_gt_f32_e32 vcc, s3, v131
	s_nop 0
	v_cndmask_b32_e64 v0, v130, v0, s[0:1]
	v_rsq_f32_e32 v130, v0
	v_mul_f32_e32 v0, 0x4b800000, v131
	v_cndmask_b32_e32 v0, v131, v0, vcc
	v_rsq_f32_e32 v131, v0
	s_nop 0
	v_pk_mul_f32 v[132:133], v[130:131], s[8:9] op_sel_hi:[1,0]
	s_nop 0
	v_cndmask_b32_e32 v141, v131, v133, vcc
	v_cndmask_b32_e64 v140, v130, v132, s[0:1]
	s_waitcnt vmcnt(1)
	v_mov_b32_e32 v130, v190
	v_mov_b32_e32 v131, v191
	v_mov_b32_e32 v132, v192
	v_mov_b32_e32 v133, v193
	v_pk_fma_f32 v[130:131], v[130:131], s[6:7], v[148:149] op_sel_hi:[1,0,0]
	s_nop 0
	v_mul_f32_e32 v0, 0x4b800000, v130
	v_cmp_gt_f32_e64 s[0:1], s3, v130
	v_cmp_gt_f32_e32 vcc, s3, v131
	s_nop 0
	v_cndmask_b32_e64 v0, v130, v0, s[0:1]
	v_rsq_f32_e32 v130, v0
	v_mul_f32_e32 v0, 0x4b800000, v131
	v_cndmask_b32_e32 v0, v131, v0, vcc
	v_rsq_f32_e32 v131, v0
	s_nop 0
	v_pk_mul_f32 v[134:135], v[130:131], s[8:9] op_sel_hi:[1,0]
	s_nop 0
	v_cndmask_b32_e32 v135, v131, v135, vcc
	v_cndmask_b32_e64 v134, v130, v134, s[0:1]
	v_pk_fma_f32 v[130:131], v[132:133], s[6:7], v[148:149] op_sel_hi:[1,0,0]
	s_nop 0
	v_mul_f32_e32 v0, 0x4b800000, v130
	v_cmp_gt_f32_e64 s[0:1], s3, v130
	v_cmp_gt_f32_e32 vcc, s3, v131
	s_nop 0
	v_cndmask_b32_e64 v0, v130, v0, s[0:1]
	v_rsq_f32_e32 v130, v0
	v_mul_f32_e32 v0, 0x4b800000, v131
	v_cndmask_b32_e32 v0, v131, v0, vcc
	v_rsq_f32_e32 v131, v0
	s_nop 0
	v_pk_mul_f32 v[132:133], v[130:131], s[8:9] op_sel_hi:[1,0]
	s_nop 0
	v_cndmask_b32_e32 v137, v131, v133, vcc
	v_cndmask_b32_e64 v136, v130, v132, s[0:1]
	s_waitcnt vmcnt(0)
	v_mov_b32_e32 v130, v194
	v_mov_b32_e32 v131, v195
	v_mov_b32_e32 v132, v196
	v_mov_b32_e32 v133, v197
	v_pk_fma_f32 v[130:131], v[130:131], s[6:7], v[148:149] op_sel_hi:[1,0,0]
	s_nop 0
	v_mul_f32_e32 v0, 0x4b800000, v130
	v_cmp_gt_f32_e64 s[0:1], s3, v130
	v_cmp_gt_f32_e32 vcc, s3, v131
	v_pk_fma_f32 v[132:133], v[132:133], s[6:7], v[148:149] op_sel_hi:[1,0,0]
	v_cndmask_b32_e64 v0, v130, v0, s[0:1]
	v_rsq_f32_e32 v130, v0
	v_mul_f32_e32 v0, 0x4b800000, v131
	v_cndmask_b32_e32 v0, v131, v0, vcc
	v_rsq_f32_e32 v131, v0
	v_mul_f32_e32 v0, 0x4b800000, v132
	v_pk_mul_f32 v[146:147], v[130:131], s[8:9] op_sel_hi:[1,0]
	s_nop 0
	v_cndmask_b32_e64 v130, v130, v146, s[0:1]
	v_cmp_gt_f32_e64 s[0:1], s3, v132
	v_cndmask_b32_e32 v131, v131, v147, vcc
	v_cmp_gt_f32_e32 vcc, s3, v133
	v_cndmask_b32_e64 v0, v132, v0, s[0:1]
	v_rsq_f32_e32 v132, v0
	v_mul_f32_e32 v0, 0x4b800000, v133
	v_cndmask_b32_e32 v0, v133, v0, vcc
	v_rsq_f32_e32 v133, v0
	s_nop 0
	v_pk_mul_f32 v[146:147], v[132:133], s[8:9] op_sel_hi:[1,0]
	s_nop 0
	v_cndmask_b32_e64 v132, v132, v146, s[0:1]
	s_cselect_b64 s[0:1], -1, 0
	s_and_b64 s[6:7], s[0:1], exec
	s_cselect_b32 s2, 0x700, s2
	s_lshl_b32 s3, s38, 8
	s_add_i32 s3, s3, s62
	v_add_u32_e32 v146, s3, v215
	v_add_u32_e32 v182, 16, v146
	s_movk_i32 s3, 0x300
	v_cndmask_b32_e32 v133, v133, v147, vcc
	v_cmp_gt_i32_e32 vcc, s3, v182
	v_add_u32_e32 v178, 32, v146
	v_add_u32_e32 v174, 48, v146
	v_cndmask_b32_e32 v0, 0, v182, vcc
	v_add_u32_e32 v148, s2, v0
	v_ashrrev_i32_e32 v149, 31, v148
	v_cmp_gt_i32_e32 vcc, s3, v178
	v_lshl_add_u64 v[148:149], v[148:149], 2, s[48:49]
	global_load_dword v184, v[148:149], off
	v_cndmask_b32_e32 v0, 0, v178, vcc
	v_add_u32_e32 v148, s2, v0
	v_ashrrev_i32_e32 v149, 31, v148
	v_cmp_gt_i32_e32 vcc, s3, v174
	v_lshl_add_u64 v[148:149], v[148:149], 2, s[48:49]
	global_load_dword v180, v[148:149], off
	v_cndmask_b32_e32 v0, 0, v174, vcc
	v_add_u32_e32 v148, s2, v0
	v_add_u32_e32 v170, 0x80, v146
	v_ashrrev_i32_e32 v149, 31, v148
	v_cmp_gt_i32_e32 vcc, s3, v170
	v_lshl_add_u64 v[148:149], v[148:149], 2, s[48:49]
	global_load_dword v176, v[148:149], off
	v_cndmask_b32_e32 v0, 0, v170, vcc
	v_add_u32_e32 v148, s2, v0
	v_add_u32_e32 v158, 0x90, v146
	v_ashrrev_i32_e32 v149, 31, v148
	v_cmp_gt_i32_e32 vcc, s3, v158
	v_lshl_add_u64 v[148:149], v[148:149], 2, s[48:49]
	global_load_dword v172, v[148:149], off
	v_cndmask_b32_e32 v0, 0, v158, vcc
	v_add_u32_e32 v148, s2, v0
	v_add_u32_e32 v154, 0xa0, v146
	v_ashrrev_i32_e32 v149, 31, v148
	v_cmp_gt_i32_e32 vcc, s3, v154
	v_lshl_add_u64 v[148:149], v[148:149], 2, s[48:49]
	global_load_dword v160, v[148:149], off
	v_cndmask_b32_e32 v0, 0, v154, vcc
	v_add_u32_e32 v148, s2, v0
	v_ashrrev_i32_e32 v149, 31, v148
	v_lshl_add_u64 v[148:149], v[148:149], 2, s[48:49]
	global_load_dword v156, v[148:149], off
	v_add_u32_e32 v148, 0xb0, v146
	v_cmp_gt_i32_e32 vcc, s3, v148
	s_movk_i32 s3, 0x280
	s_nop 0
	v_cndmask_b32_e32 v0, 0, v148, vcc
	v_add_u32_e32 v152, s2, v0
	v_ashrrev_i32_e32 v153, 31, v152
	v_lshl_add_u64 v[152:153], v[152:153], 2, s[48:49]
	global_load_dword v152, v[152:153], off
	v_add_u32_e32 v0, s63, v150
	v_add_u32_e32 v150, s4, v0
	v_cndmask_b32_e64 v0, 0, 1, s[0:1]
	v_cmp_gt_i32_e32 vcc, s3, v146
	v_ashrrev_i32_e32 v151, 31, v150
	v_cmp_ne_u32_e64 s[36:37], 1, v0
	s_and_saveexec_b64 s[4:5], vcc
	s_cbranch_execz .LBB0_175
	v_add_u32_e32 v186, s2, v146
	v_ashrrev_i32_e32 v187, 31, v186
	v_lshl_add_u64 v[186:187], v[186:187], 2, s[48:49]
	global_load_dword v186, v[186:187], off
	v_mov_b64_e32 v[188:189], s[44:45]
	s_movk_i32 s0, 0x1ff
	v_mad_i64_i32 v[188:189], s[2:3], v146, s39, v[188:189]
	v_ashrrev_i32_e32 v147, 31, v146
	v_cmp_lt_i32_e64 s[0:1], s0, v146
	v_mov_b32_e32 v0, v146
	v_lshl_add_u64 v[188:189], v[150:151], 1, v[188:189]
	s_and_b64 vcc, exec, s[36:37]
	s_waitcnt vmcnt(0)
	v_pk_fma_f32 v[190:191], v[128:129], v[144:145], v[186:187] op_sel_hi:[1,1,0]
	v_pk_fma_f32 v[192:193], v[126:127], v[142:143], v[186:187] op_sel_hi:[1,1,0]
	v_cvt_pk_bf16_f32 v195, v190, v191
	v_cvt_pk_bf16_f32 v194, v192, v193
	global_store_dwordx2 v[188:189], v[194:195], off
	s_cbranch_vccnz .LBB0_158
	s_and_saveexec_b64 s[2:3], s[0:1]
	s_xor_b64 s[6:7], exec, s[2:3]
	s_cbranch_execz .LBB0_155
	v_readlane_b32 s88, v252, 3
	v_lshlrev_b64 v[194:195], 9, v[150:151]
	v_readlane_b32 s94, v252, 9
	v_readlane_b32 s95, v252, 10
	v_readlane_b32 s89, v252, 4
	v_readlane_b32 s90, v252, 5
	v_lshl_add_u64 v[194:195], s[94:95], 0, v[194:195]
	v_lshl_add_u64 v[194:195], v[0:1], 2, v[194:195]
	v_add_co_u32_e32 v194, vcc, 0x53ff000, v194
	v_readlane_b32 s93, v252, 8
	s_nop 0
	v_addc_co_u32_e32 v195, vcc, 0, v195, vcc
	v_readlane_b32 s91, v252, 6
	v_readlane_b32 s92, v252, 7
	s_mov_b32 s93, 0x1b000
	s_mov_b32 s90, 0xe1000
	s_mov_b32 s89, 0xc6000
	s_mov_b32 s88, 0x7e000
	global_store_dword v[194:195], v192, off offset:2048
	global_store_dword v[194:195], v193, off offset:2560
	global_store_dword v[194:195], v190, off offset:3072
	global_store_dword v[194:195], v191, off offset:3584

.LBB0_462:
	s_add_i32 s30, s37, 2
	s_or_b32 s82, s37, 1
	s_lshl_b64 s[12:13], s[30:31], 7
	s_add_u32 s83, s4, s12
	s_addc_u32 s84, s5, s13
	s_add_u32 s86, s6, s12
	s_addc_u32 s85, s7, s13
	s_add_i32 s87, 0, 0x10000
	s_cmp_eq_u32 s37, s72
	s_cselect_b32 s13, s63, s84
	s_cselect_b32 s12, s62, s83
	s_cselect_b32 s85, s65, s85
	s_cselect_b32 s84, s64, s86
	s_add_i32 s37, 0, 0x14000
	v_add_u32_e32 v142, s87, v208
	v_add_u32_e32 v158, s37, v208
	ds_read_b128 v[130:133], v142
	ds_read_b128 v[134:137], v142 offset:1024
	ds_read_b128 v[138:141], v142 offset:2048
	ds_read_b128 v[142:145], v142 offset:3072
	ds_read_b128 v[146:149], v158
	ds_read_b128 v[150:153], v158 offset:1024
	ds_read_b128 v[154:157], v158 offset:2048
	ds_read_b128 v[158:161], v158 offset:3072
	s_mov_b32 s83, s31
	s_lshl_b64 s[82:83], s[82:83], 7
	s_add_u32 s82, s33, s82
	s_addc_u32 s83, s36, s83
	v_lshl_add_u64 v[194:195], s[82:83], 0, v[0:1]
	s_add_i32 m0, s20, 0xc000
	ds_read_b128 v[162:165], v209
	ds_read_b128 v[166:169], v209 offset:1024
	ds_read_b128 v[170:173], v209 offset:2048
	ds_read_b128 v[174:177], v209 offset:3072
	ds_read_b128 v[178:181], v209 offset:4096
	ds_read_b128 v[182:185], v209 offset:5120
	ds_read_b128 v[186:189], v209 offset:6144
	ds_read_b128 v[190:193], v209 offset:7168
	global_load_lds_dwordx4 v[194:195], off
	v_lshl_add_u64 v[194:195], s[82:83], 0, v[216:217]
	s_add_i32 m0, s20, 0xe000
	s_nop 0
	global_load_lds_dwordx4 v[194:195], off
	s_waitcnt vmcnt(8)
	s_waitcnt lgkmcnt(0)
	s_barrier
	s_setprio 1
	s_waitcnt lgkmcnt(0)
	v_mfma_f32_16x16x32_bf16 v[126:129], v[130:133], v[162:165], v[126:129]
	v_mfma_f32_16x16x32_bf16 v[122:125], v[138:141], v[162:165], v[122:125]
	v_mfma_f32_16x16x32_bf16 v[110:113], v[130:133], v[170:173], v[110:113]
	v_mfma_f32_16x16x32_bf16 v[106:109], v[138:141], v[170:173], v[106:109]
	v_mfma_f32_16x16x32_bf16 v[94:97], v[130:133], v[178:181], v[94:97]
	v_mfma_f32_16x16x32_bf16 v[90:93], v[138:141], v[178:181], v[90:93]
	v_mfma_f32_16x16x32_bf16 v[78:81], v[130:133], v[186:189], v[78:81]
	v_mfma_f32_16x16x32_bf16 v[74:77], v[138:141], v[186:189], v[74:77]
	v_mfma_f32_16x16x32_bf16 v[126:129], v[134:137], v[166:169], v[126:129]
	v_mfma_f32_16x16x32_bf16 v[122:125], v[142:145], v[166:169], v[122:125]
	v_mfma_f32_16x16x32_bf16 v[110:113], v[134:137], v[174:177], v[110:113]
	v_mfma_f32_16x16x32_bf16 v[106:109], v[142:145], v[174:177], v[106:109]
	v_mfma_f32_16x16x32_bf16 v[94:97], v[134:137], v[182:185], v[94:97]
	v_mfma_f32_16x16x32_bf16 v[90:93], v[142:145], v[182:185], v[90:93]
	v_mfma_f32_16x16x32_bf16 v[78:81], v[134:137], v[190:193], v[78:81]
	v_mfma_f32_16x16x32_bf16 v[74:77], v[142:145], v[190:193], v[74:77]
	s_setprio 0
	s_setprio 1
	v_mfma_f32_16x16x32_bf16 v[118:121], v[146:149], v[162:165], v[118:121]
	v_mfma_f32_16x16x32_bf16 v[114:117], v[154:157], v[162:165], v[114:117]
	v_mfma_f32_16x16x32_bf16 v[102:105], v[146:149], v[170:173], v[102:105]
	v_mfma_f32_16x16x32_bf16 v[98:101], v[154:157], v[170:173], v[98:101]
	v_mfma_f32_16x16x32_bf16 v[86:89], v[146:149], v[178:181], v[86:89]
	v_mfma_f32_16x16x32_bf16 v[82:85], v[154:157], v[178:181], v[82:85]
	v_mfma_f32_16x16x32_bf16 v[70:73], v[146:149], v[186:189], v[70:73]
	v_mfma_f32_16x16x32_bf16 v[66:69], v[154:157], v[186:189], v[66:69]
	v_mfma_f32_16x16x32_bf16 v[118:121], v[150:153], v[166:169], v[118:121]
	v_mfma_f32_16x16x32_bf16 v[114:117], v[158:161], v[166:169], v[114:117]
	v_mfma_f32_16x16x32_bf16 v[102:105], v[150:153], v[174:177], v[102:105]
	v_mfma_f32_16x16x32_bf16 v[98:101], v[158:161], v[174:177], v[98:101]
	v_mfma_f32_16x16x32_bf16 v[86:89], v[150:153], v[182:185], v[86:89]
	v_mfma_f32_16x16x32_bf16 v[82:85], v[158:161], v[182:185], v[82:85]
	v_mfma_f32_16x16x32_bf16 v[70:73], v[150:153], v[190:193], v[70:73]
	v_mfma_f32_16x16x32_bf16 v[66:69], v[158:161], v[190:193], v[66:69]
	s_setprio 0
	s_barrier
	s_add_i32 s82, s87, s19
	v_lshl_add_u64 v[194:195], s[84:85], 0, v[0:1]
	s_mov_b32 m0, s82
	ds_read_b128 v[162:165], v209 offset:16384
	ds_read_b128 v[166:169], v209 offset:17408
	ds_read_b128 v[170:173], v209 offset:18432
	ds_read_b128 v[174:177], v209 offset:19456
	ds_read_b128 v[178:181], v209 offset:20480
	ds_read_b128 v[182:185], v209 offset:21504
	ds_read_b128 v[186:189], v209 offset:22528
	ds_read_b128 v[190:193], v209 offset:23552
	global_load_lds_dwordx4 v[194:195], off
	s_add_i32 m0, s82, 0x2000
	s_add_u32 s82, s84, s18
	v_lshl_add_u64 v[196:197], s[84:85], 0, v[216:217]
	s_addc_u32 s83, s85, 0
	s_add_i32 s37, s37, s19
	global_load_lds_dwordx4 v[196:197], off
	v_lshl_add_u64 v[198:199], s[82:83], 0, v[0:1]
	s_mov_b32 m0, s37
	v_lshl_add_u64 v[200:201], s[82:83], 0, v[216:217]
	global_load_lds_dwordx4 v[198:199], off
	s_add_i32 m0, s37, 0x2000
	v_lshl_add_u64 v[222:223], s[12:13], 0, v[0:1]
	global_load_lds_dwordx4 v[200:201], off
	s_mov_b32 m0, s20
	v_lshl_add_u64 v[224:225], s[12:13], 0, v[216:217]
	global_load_lds_dwordx4 v[222:223], off
	s_mov_b32 m0, s21
	s_nop 0
	global_load_lds_dwordx4 v[224:225], off
	s_waitcnt vmcnt(8)
	s_waitcnt lgkmcnt(0)
	s_barrier
	s_setprio 1
	s_waitcnt lgkmcnt(0)
	v_mfma_f32_16x16x32_bf16 v[62:65], v[130:133], v[162:165], v[62:65]
	v_mfma_f32_16x16x32_bf16 v[58:61], v[138:141], v[162:165], v[58:61]
	v_mfma_f32_16x16x32_bf16 v[46:49], v[130:133], v[170:173], v[46:49]
	v_mfma_f32_16x16x32_bf16 v[42:45], v[138:141], v[170:173], v[42:45]
	v_mfma_f32_16x16x32_bf16 v[30:33], v[130:133], v[178:181], v[30:33]
	v_mfma_f32_16x16x32_bf16 v[26:29], v[138:141], v[178:181], v[26:29]
	v_mfma_f32_16x16x32_bf16 v[14:17], v[130:133], v[186:189], v[14:17]
	v_mfma_f32_16x16x32_bf16 v[10:13], v[138:141], v[186:189], v[10:13]
	v_mfma_f32_16x16x32_bf16 v[62:65], v[134:137], v[166:169], v[62:65]
	v_mfma_f32_16x16x32_bf16 v[58:61], v[142:145], v[166:169], v[58:61]
	v_mfma_f32_16x16x32_bf16 v[46:49], v[134:137], v[174:177], v[46:49]
	v_mfma_f32_16x16x32_bf16 v[42:45], v[142:145], v[174:177], v[42:45]
	v_mfma_f32_16x16x32_bf16 v[30:33], v[134:137], v[182:185], v[30:33]
	v_mfma_f32_16x16x32_bf16 v[26:29], v[142:145], v[182:185], v[26:29]
	v_mfma_f32_16x16x32_bf16 v[14:17], v[134:137], v[190:193], v[14:17]
	v_mfma_f32_16x16x32_bf16 v[10:13], v[142:145], v[190:193], v[10:13]
	s_setprio 0
	s_setprio 1
	v_mfma_f32_16x16x32_bf16 v[54:57], v[146:149], v[162:165], v[54:57]
	v_mfma_f32_16x16x32_bf16 v[50:53], v[154:157], v[162:165], v[50:53]
	v_mfma_f32_16x16x32_bf16 v[38:41], v[146:149], v[170:173], v[38:41]
	v_mfma_f32_16x16x32_bf16 v[34:37], v[154:157], v[170:173], v[34:37]
	v_mfma_f32_16x16x32_bf16 v[22:25], v[146:149], v[178:181], v[22:25]
	v_mfma_f32_16x16x32_bf16 v[18:21], v[154:157], v[178:181], v[18:21]
	v_mfma_f32_16x16x32_bf16 v[6:9], v[146:149], v[186:189], v[6:9]
	v_mfma_f32_16x16x32_bf16 v[2:5], v[154:157], v[186:189], v[2:5]
	v_mfma_f32_16x16x32_bf16 v[54:57], v[150:153], v[166:169], v[54:57]
	v_mfma_f32_16x16x32_bf16 v[50:53], v[158:161], v[166:169], v[50:53]
	v_mfma_f32_16x16x32_bf16 v[38:41], v[150:153], v[174:177], v[38:41]
	v_mfma_f32_16x16x32_bf16 v[34:37], v[158:161], v[174:177], v[34:37]
	v_mfma_f32_16x16x32_bf16 v[22:25], v[150:153], v[182:185], v[22:25]
	v_mfma_f32_16x16x32_bf16 v[18:21], v[158:161], v[182:185], v[18:21]
	v_mfma_f32_16x16x32_bf16 v[6:9], v[150:153], v[190:193], v[6:9]
	v_mfma_f32_16x16x32_bf16 v[2:5], v[158:161], v[190:193], v[2:5]
	s_setprio 0
	s_barrier
	s_add_i32 s37, 0, 0x18000
	s_add_i32 s82, 0, 0x1c000
	v_add_u32_e32 v142, s37, v208
	v_add_u32_e32 v158, s82, v208
	ds_read_b128 v[130:133], v142
	ds_read_b128 v[134:137], v142 offset:1024
	ds_read_b128 v[138:141], v142 offset:2048
	ds_read_b128 v[142:145], v142 offset:3072
	ds_read_b128 v[146:149], v158
	ds_read_b128 v[150:153], v158 offset:1024
	ds_read_b128 v[154:157], v158 offset:2048
	ds_read_b128 v[158:161], v158 offset:3072
	s_add_u32 s12, s12, s18
	s_addc_u32 s13, s13, 0
	s_mov_b32 m0, s22
	v_lshl_add_u64 v[226:227], s[12:13], 0, v[0:1]
	ds_read_b128 v[162:165], v209 offset:32768
	ds_read_b128 v[166:169], v209 offset:33792
	ds_read_b128 v[170:173], v209 offset:34816
	ds_read_b128 v[174:177], v209 offset:35840
	ds_read_b128 v[178:181], v209 offset:36864
	ds_read_b128 v[182:185], v209 offset:37888
	ds_read_b128 v[186:189], v209 offset:38912
	ds_read_b128 v[190:193], v209 offset:39936
	global_load_lds_dwordx4 v[226:227], off
	v_lshl_add_u64 v[226:227], s[12:13], 0, v[216:217]
	s_mov_b32 m0, s23
	s_nop 0
	global_load_lds_dwordx4 v[226:227], off
	s_waitcnt vmcnt(8)
	s_waitcnt lgkmcnt(0)
	s_barrier
	s_setprio 1
	s_waitcnt lgkmcnt(0)
	v_mfma_f32_16x16x32_bf16 v[126:129], v[130:133], v[162:165], v[126:129]
	v_mfma_f32_16x16x32_bf16 v[122:125], v[138:141], v[162:165], v[122:125]
	v_mfma_f32_16x16x32_bf16 v[110:113], v[130:133], v[170:173], v[110:113]
	v_mfma_f32_16x16x32_bf16 v[106:109], v[138:141], v[170:173], v[106:109]
	v_mfma_f32_16x16x32_bf16 v[94:97], v[130:133], v[178:181], v[94:97]
	v_mfma_f32_16x16x32_bf16 v[90:93], v[138:141], v[178:181], v[90:93]
	v_mfma_f32_16x16x32_bf16 v[78:81], v[130:133], v[186:189], v[78:81]
	v_mfma_f32_16x16x32_bf16 v[74:77], v[138:141], v[186:189], v[74:77]
	v_mfma_f32_16x16x32_bf16 v[126:129], v[134:137], v[166:169], v[126:129]
	v_mfma_f32_16x16x32_bf16 v[122:125], v[142:145], v[166:169], v[122:125]
	v_mfma_f32_16x16x32_bf16 v[110:113], v[134:137], v[174:177], v[110:113]
	v_mfma_f32_16x16x32_bf16 v[106:109], v[142:145], v[174:177], v[106:109]
	v_mfma_f32_16x16x32_bf16 v[94:97], v[134:137], v[182:185], v[94:97]
	v_mfma_f32_16x16x32_bf16 v[90:93], v[142:145], v[182:185], v[90:93]
	v_mfma_f32_16x16x32_bf16 v[78:81], v[134:137], v[190:193], v[78:81]
	v_mfma_f32_16x16x32_bf16 v[74:77], v[142:145], v[190:193], v[74:77]
	s_setprio 0
	s_setprio 1
	v_mfma_f32_16x16x32_bf16 v[118:121], v[146:149], v[162:165], v[118:121]
	v_mfma_f32_16x16x32_bf16 v[114:117], v[154:157], v[162:165], v[114:117]
	v_mfma_f32_16x16x32_bf16 v[102:105], v[146:149], v[170:173], v[102:105]
	v_mfma_f32_16x16x32_bf16 v[98:101], v[154:157], v[170:173], v[98:101]
	v_mfma_f32_16x16x32_bf16 v[86:89], v[146:149], v[178:181], v[86:89]
	v_mfma_f32_16x16x32_bf16 v[82:85], v[154:157], v[178:181], v[82:85]
	v_mfma_f32_16x16x32_bf16 v[70:73], v[146:149], v[186:189], v[70:73]
	v_mfma_f32_16x16x32_bf16 v[66:69], v[154:157], v[186:189], v[66:69]
	v_mfma_f32_16x16x32_bf16 v[118:121], v[150:153], v[166:169], v[118:121]
	v_mfma_f32_16x16x32_bf16 v[114:117], v[158:161], v[166:169], v[114:117]
	v_mfma_f32_16x16x32_bf16 v[102:105], v[150:153], v[174:177], v[102:105]
	v_mfma_f32_16x16x32_bf16 v[98:101], v[158:161], v[174:177], v[98:101]
	v_mfma_f32_16x16x32_bf16 v[86:89], v[150:153], v[182:185], v[86:89]
	v_mfma_f32_16x16x32_bf16 v[82:85], v[158:161], v[182:185], v[82:85]
	v_mfma_f32_16x16x32_bf16 v[70:73], v[150:153], v[190:193], v[70:73]
	v_mfma_f32_16x16x32_bf16 v[66:69], v[158:161], v[190:193], v[66:69]
	s_setprio 0
	s_barrier
	s_add_i32 s12, s37, s19
	v_lshl_add_u64 v[194:195], v[194:195], 0, s[96:97]
	s_mov_b32 m0, s12
	ds_read_b128 v[162:165], v209 offset:49152
	ds_read_b128 v[166:169], v209 offset:50176
	ds_read_b128 v[170:173], v209 offset:51200
	ds_read_b128 v[174:177], v209 offset:52224
	ds_read_b128 v[178:181], v209 offset:53248
	ds_read_b128 v[182:185], v209 offset:54272
	ds_read_b128 v[186:189], v209 offset:55296
	ds_read_b128 v[190:193], v209 offset:56320
	global_load_lds_dwordx4 v[194:195], off
	v_lshl_add_u64 v[194:195], v[196:197], 0, s[96:97]
	s_add_i32 m0, s12, 0x2000
	s_add_i32 s12, s82, s19
	global_load_lds_dwordx4 v[194:195], off
	v_lshl_add_u64 v[194:195], v[198:199], 0, s[96:97]
	s_mov_b32 m0, s12
	s_nop 0
	global_load_lds_dwordx4 v[194:195], off
	v_lshl_add_u64 v[194:195], v[200:201], 0, s[96:97]
	s_add_i32 m0, s12, 0x2000
	s_nop 0
	global_load_lds_dwordx4 v[194:195], off
	v_lshl_add_u64 v[194:195], v[222:223], 0, s[96:97]
	s_mov_b32 m0, s69
	s_nop 0
	global_load_lds_dwordx4 v[194:195], off
	v_lshl_add_u64 v[194:195], v[224:225], 0, s[96:97]
	s_mov_b32 m0, s70
	s_nop 0
	global_load_lds_dwordx4 v[194:195], off
	s_waitcnt vmcnt(8)
	s_waitcnt lgkmcnt(0)
	s_barrier
	s_setprio 1
	s_waitcnt lgkmcnt(0)
	v_mfma_f32_16x16x32_bf16 v[62:65], v[130:133], v[162:165], v[62:65]
	v_mfma_f32_16x16x32_bf16 v[58:61], v[138:141], v[162:165], v[58:61]
	v_mfma_f32_16x16x32_bf16 v[46:49], v[130:133], v[170:173], v[46:49]
	v_mfma_f32_16x16x32_bf16 v[42:45], v[138:141], v[170:173], v[42:45]
	v_mfma_f32_16x16x32_bf16 v[30:33], v[130:133], v[178:181], v[30:33]
	v_mfma_f32_16x16x32_bf16 v[26:29], v[138:141], v[178:181], v[26:29]
	v_mfma_f32_16x16x32_bf16 v[14:17], v[130:133], v[186:189], v[14:17]
	v_mfma_f32_16x16x32_bf16 v[10:13], v[138:141], v[186:189], v[10:13]
	v_mfma_f32_16x16x32_bf16 v[62:65], v[134:137], v[166:169], v[62:65]
	v_mfma_f32_16x16x32_bf16 v[58:61], v[142:145], v[166:169], v[58:61]
	v_mfma_f32_16x16x32_bf16 v[46:49], v[134:137], v[174:177], v[46:49]
	v_mfma_f32_16x16x32_bf16 v[42:45], v[142:145], v[174:177], v[42:45]
	v_mfma_f32_16x16x32_bf16 v[30:33], v[134:137], v[182:185], v[30:33]
	v_mfma_f32_16x16x32_bf16 v[26:29], v[142:145], v[182:185], v[26:29]
	v_mfma_f32_16x16x32_bf16 v[14:17], v[134:137], v[190:193], v[14:17]
	v_mfma_f32_16x16x32_bf16 v[10:13], v[142:145], v[190:193], v[10:13]
	s_setprio 0
	s_setprio 1
	v_mfma_f32_16x16x32_bf16 v[54:57], v[146:149], v[162:165], v[54:57]
	v_mfma_f32_16x16x32_bf16 v[50:53], v[154:157], v[162:165], v[50:53]
	v_mfma_f32_16x16x32_bf16 v[38:41], v[146:149], v[170:173], v[38:41]
	v_mfma_f32_16x16x32_bf16 v[34:37], v[154:157], v[170:173], v[34:37]
	v_mfma_f32_16x16x32_bf16 v[22:25], v[146:149], v[178:181], v[22:25]
	v_mfma_f32_16x16x32_bf16 v[18:21], v[154:157], v[178:181], v[18:21]
	v_mfma_f32_16x16x32_bf16 v[6:9], v[146:149], v[186:189], v[6:9]
	v_mfma_f32_16x16x32_bf16 v[2:5], v[154:157], v[186:189], v[2:5]
	v_mfma_f32_16x16x32_bf16 v[54:57], v[150:153], v[166:169], v[54:57]
	v_mfma_f32_16x16x32_bf16 v[50:53], v[158:161], v[166:169], v[50:53]
	v_mfma_f32_16x16x32_bf16 v[38:41], v[150:153], v[174:177], v[38:41]
	v_mfma_f32_16x16x32_bf16 v[34:37], v[158:161], v[174:177], v[34:37]
	v_mfma_f32_16x16x32_bf16 v[22:25], v[150:153], v[182:185], v[22:25]
	v_mfma_f32_16x16x32_bf16 v[18:21], v[158:161], v[182:185], v[18:21]
	v_mfma_f32_16x16x32_bf16 v[6:9], v[150:153], v[190:193], v[6:9]
	v_mfma_f32_16x16x32_bf16 v[2:5], v[158:161], v[190:193], v[2:5]
	s_setprio 0
	s_barrier
	s_cmp_ge_u32 s30, s27
	s_mov_b32 s37, s30
	s_cbranch_scc1 .LBB0_473

.LBB0_481:
	v_add_u32_e32 v162, 32, v224
	v_ashrrev_i32_e32 v163, 31, v162
	v_lshlrev_b64 v[164:165], 12, v[162:163]
	v_lshl_add_u64 v[114:115], v[244:245], 0, v[164:165]
	global_load_dwordx4 v[126:129], v[114:115], off
	global_load_dwordx4 v[122:125], v[114:115], off offset:64
	global_load_dwordx4 v[118:121], v[114:115], off offset:512
	s_nop 0
	global_load_dwordx4 v[114:117], v[114:115], off offset:576
	v_readlane_b32 s4, v252, 3
	v_readlane_b32 s10, v252, 9
	v_readlane_b32 s11, v252, 10
	v_readlane_b32 s5, v252, 4
	s_and_b64 vcc, exec, s[54:55]
	s_cbranch_vccz .Leprv_0
	s_waitcnt vmcnt(8)
.Leprv_0:
	s_waitcnt vmcnt(16)
	v_pk_fma_f32 v[152:153], v[112:113], v[232:233], v[144:145]
	v_lshl_add_u64 v[146:147], s[10:11], 0, v[248:249]
	v_pk_fma_f32 v[150:151], v[110:111], v[234:235], v[142:143]
	v_lshl_add_u64 v[172:173], v[222:223], 2, v[146:147]
	s_mov_b64 s[4:5], -1
	s_and_b64 vcc, exec, s[54:55]
	s_waitcnt vmcnt(15)
	v_pk_fma_f32 v[146:147], v[106:107], v[236:237], v[138:139]
	s_waitcnt vmcnt(14)
	v_pk_fma_f32 v[142:143], v[102:103], v[238:239], v[134:135]
	s_waitcnt vmcnt(13)
	v_pk_fma_f32 v[110:111], v[98:99], v[240:241], v[130:131]
	v_readlane_b32 s6, v252, 5
	v_readlane_b32 s7, v252, 6
	v_readlane_b32 s8, v252, 7
	v_readlane_b32 s9, v252, 8
	global_store_dwordx4 v[172:173], v[150:153], off
	s_cbranch_vccz .LBB0_483
	v_pk_fma_f32 v[148:149], v[108:109], v[230:231], v[140:141]
	v_pk_fma_f32 v[144:145], v[104:105], v[228:229], v[136:137]
	v_pk_fma_f32 v[112:113], v[100:101], v[226:227], v[132:133]
	global_store_dwordx4 v[172:173], v[146:149], off offset:64
	global_store_dwordx4 v[172:173], v[142:145], off offset:512
	global_store_dwordx4 v[172:173], v[110:113], off offset:576
	s_mov_b64 s[4:5], 0

.LBB0_487:
	v_add_u32_e32 v138, 48, v224
	v_ashrrev_i32_e32 v139, 31, v138
	v_lshlrev_b64 v[140:141], 12, v[138:139]
	v_lshl_add_u64 v[98:99], v[244:245], 0, v[140:141]
	global_load_dwordx4 v[110:113], v[98:99], off
	global_load_dwordx4 v[106:109], v[98:99], off offset:64
	global_load_dwordx4 v[102:105], v[98:99], off offset:512
	s_nop 0
	global_load_dwordx4 v[98:101], v[98:99], off offset:576
	v_readlane_b32 s4, v252, 3
	v_readlane_b32 s10, v252, 9
	v_readlane_b32 s11, v252, 10
	v_readlane_b32 s5, v252, 4
	s_and_b64 vcc, exec, s[54:55]
	s_cbranch_vccz .Leprv_1
	s_waitcnt vmcnt(8)
.Leprv_1:
	s_waitcnt vmcnt(16)
	v_pk_fma_f32 v[136:137], v[96:97], v[232:233], v[128:129]
	v_lshl_add_u64 v[130:131], s[10:11], 0, v[164:165]
	v_pk_fma_f32 v[134:135], v[94:95], v[234:235], v[126:127]
	v_lshl_add_u64 v[142:143], v[222:223], 2, v[130:131]
	s_mov_b64 s[4:5], -1
	s_and_b64 vcc, exec, s[54:55]
	s_waitcnt vmcnt(15)
	v_pk_fma_f32 v[130:131], v[90:91], v[236:237], v[122:123]
	s_waitcnt vmcnt(14)
	v_pk_fma_f32 v[126:127], v[86:87], v[238:239], v[118:119]
	s_waitcnt vmcnt(13)
	v_pk_fma_f32 v[94:95], v[82:83], v[240:241], v[114:115]
	v_readlane_b32 s6, v252, 5
	v_readlane_b32 s7, v252, 6
	v_readlane_b32 s8, v252, 7
	v_readlane_b32 s9, v252, 8
	global_store_dwordx4 v[142:143], v[134:137], off
	s_cbranch_vccz .LBB0_489
	v_pk_fma_f32 v[132:133], v[92:93], v[230:231], v[124:125]
	v_pk_fma_f32 v[128:129], v[88:89], v[228:229], v[120:121]
	v_pk_fma_f32 v[96:97], v[84:85], v[226:227], v[116:117]
	global_store_dwordx4 v[142:143], v[130:133], off offset:64
	global_store_dwordx4 v[142:143], v[126:129], off offset:512
	global_store_dwordx4 v[142:143], v[94:97], off offset:576
	s_mov_b64 s[4:5], 0

.LBB0_493:
	v_add_u32_e32 v122, 0x80, v224
	v_ashrrev_i32_e32 v123, 31, v122
	v_lshlrev_b64 v[124:125], 12, v[122:123]
	v_lshl_add_u64 v[82:83], v[244:245], 0, v[124:125]
	global_load_dwordx4 v[94:97], v[82:83], off
	global_load_dwordx4 v[90:93], v[82:83], off offset:64
	global_load_dwordx4 v[86:89], v[82:83], off offset:512
	s_nop 0
	global_load_dwordx4 v[82:85], v[82:83], off offset:576
	v_readlane_b32 s4, v252, 3
	v_readlane_b32 s10, v252, 9
	v_readlane_b32 s11, v252, 10
	v_readlane_b32 s5, v252, 4
	s_and_b64 vcc, exec, s[54:55]
	s_cbranch_vccz .Leprv_2
	s_waitcnt vmcnt(8)
.Leprv_2:
	s_waitcnt vmcnt(16)
	v_pk_fma_f32 v[120:121], v[80:81], v[232:233], v[112:113]
	v_lshl_add_u64 v[114:115], s[10:11], 0, v[140:141]
	v_pk_fma_f32 v[118:119], v[78:79], v[234:235], v[110:111]
	v_lshl_add_u64 v[126:127], v[222:223], 2, v[114:115]
	s_mov_b64 s[4:5], -1
	s_and_b64 vcc, exec, s[54:55]
	s_waitcnt vmcnt(15)
	v_pk_fma_f32 v[114:115], v[74:75], v[236:237], v[106:107]
	s_waitcnt vmcnt(14)
	v_pk_fma_f32 v[110:111], v[70:71], v[238:239], v[102:103]
	s_waitcnt vmcnt(13)
	v_pk_fma_f32 v[78:79], v[66:67], v[240:241], v[98:99]
	v_readlane_b32 s6, v252, 5
	v_readlane_b32 s7, v252, 6
	v_readlane_b32 s8, v252, 7
	v_readlane_b32 s9, v252, 8
	global_store_dwordx4 v[126:127], v[118:121], off
	s_cbranch_vccz .LBB0_495
	v_pk_fma_f32 v[116:117], v[76:77], v[230:231], v[108:109]
	v_pk_fma_f32 v[112:113], v[72:73], v[228:229], v[104:105]
	v_pk_fma_f32 v[80:81], v[68:69], v[226:227], v[100:101]
	global_store_dwordx4 v[126:127], v[114:117], off offset:64
	global_store_dwordx4 v[126:127], v[110:113], off offset:512
	global_store_dwordx4 v[126:127], v[78:81], off offset:576
	s_mov_b64 s[4:5], 0

.LBB0_499:
	v_add_u32_e32 v106, 0x90, v224
	v_ashrrev_i32_e32 v107, 31, v106
	v_lshlrev_b64 v[108:109], 12, v[106:107]
	v_lshl_add_u64 v[66:67], v[244:245], 0, v[108:109]
	global_load_dwordx4 v[78:81], v[66:67], off
	global_load_dwordx4 v[74:77], v[66:67], off offset:64
	global_load_dwordx4 v[70:73], v[66:67], off offset:512
	s_nop 0
	global_load_dwordx4 v[66:69], v[66:67], off offset:576
	v_readlane_b32 s4, v252, 3
	v_readlane_b32 s10, v252, 9
	v_readlane_b32 s11, v252, 10
	v_readlane_b32 s5, v252, 4
	s_and_b64 vcc, exec, s[54:55]
	s_cbranch_vccz .Leprv_3
	s_waitcnt vmcnt(8)
.Leprv_3:
	s_waitcnt vmcnt(16)
	v_pk_fma_f32 v[104:105], v[64:65], v[232:233], v[96:97]
	v_lshl_add_u64 v[98:99], s[10:11], 0, v[124:125]
	v_pk_fma_f32 v[102:103], v[62:63], v[234:235], v[94:95]
	v_lshl_add_u64 v[110:111], v[222:223], 2, v[98:99]
	s_mov_b64 s[4:5], -1
	s_and_b64 vcc, exec, s[54:55]
	s_waitcnt vmcnt(15)
	v_pk_fma_f32 v[98:99], v[58:59], v[236:237], v[90:91]
	s_waitcnt vmcnt(14)
	v_pk_fma_f32 v[94:95], v[54:55], v[238:239], v[86:87]
	s_waitcnt vmcnt(13)
	v_pk_fma_f32 v[62:63], v[50:51], v[240:241], v[82:83]
	v_readlane_b32 s6, v252, 5
	v_readlane_b32 s7, v252, 6
	v_readlane_b32 s8, v252, 7
	v_readlane_b32 s9, v252, 8
	global_store_dwordx4 v[110:111], v[102:105], off
	s_cbranch_vccz .LBB0_501
	v_pk_fma_f32 v[100:101], v[60:61], v[230:231], v[92:93]
	v_pk_fma_f32 v[96:97], v[56:57], v[228:229], v[88:89]
	v_pk_fma_f32 v[64:65], v[52:53], v[226:227], v[84:85]
	global_store_dwordx4 v[110:111], v[98:101], off offset:64
	global_store_dwordx4 v[110:111], v[94:97], off offset:512
	global_store_dwordx4 v[110:111], v[62:65], off offset:576
	s_mov_b64 s[4:5], 0

.LBB0_505:
	v_add_u32_e32 v90, 0xa0, v224
	v_ashrrev_i32_e32 v91, 31, v90
	v_lshlrev_b64 v[92:93], 12, v[90:91]
	v_lshl_add_u64 v[50:51], v[244:245], 0, v[92:93]
	global_load_dwordx4 v[62:65], v[50:51], off
	global_load_dwordx4 v[58:61], v[50:51], off offset:64
	global_load_dwordx4 v[54:57], v[50:51], off offset:512
	s_nop 0
	global_load_dwordx4 v[50:53], v[50:51], off offset:576
	v_readlane_b32 s4, v252, 3
	v_readlane_b32 s10, v252, 9
	v_readlane_b32 s11, v252, 10
	v_readlane_b32 s5, v252, 4
	s_and_b64 vcc, exec, s[54:55]
	s_cbranch_vccz .Leprv_4
	s_waitcnt vmcnt(8)
.Leprv_4:
	s_waitcnt vmcnt(16)
	v_pk_fma_f32 v[88:89], v[48:49], v[232:233], v[80:81]
	v_lshl_add_u64 v[82:83], s[10:11], 0, v[108:109]
	v_pk_fma_f32 v[86:87], v[46:47], v[234:235], v[78:79]
	v_lshl_add_u64 v[94:95], v[222:223], 2, v[82:83]
	s_mov_b64 s[4:5], -1
	s_and_b64 vcc, exec, s[54:55]
	s_waitcnt vmcnt(15)
	v_pk_fma_f32 v[82:83], v[42:43], v[236:237], v[74:75]
	s_waitcnt vmcnt(14)
	v_pk_fma_f32 v[78:79], v[38:39], v[238:239], v[70:71]
	s_waitcnt vmcnt(13)
	v_pk_fma_f32 v[46:47], v[34:35], v[240:241], v[66:67]
	v_readlane_b32 s6, v252, 5
	v_readlane_b32 s7, v252, 6
	v_readlane_b32 s8, v252, 7
	v_readlane_b32 s9, v252, 8
	global_store_dwordx4 v[94:95], v[86:89], off
	s_cbranch_vccz .LBB0_507
	v_pk_fma_f32 v[84:85], v[44:45], v[230:231], v[76:77]
	v_pk_fma_f32 v[80:81], v[40:41], v[228:229], v[72:73]
	v_pk_fma_f32 v[48:49], v[36:37], v[226:227], v[68:69]
	global_store_dwordx4 v[94:95], v[82:85], off offset:64
	global_store_dwordx4 v[94:95], v[78:81], off offset:512
	global_store_dwordx4 v[94:95], v[46:49], off offset:576
	s_mov_b64 s[4:5], 0

.LBB0_511:
	v_add_u32_e32 v74, 0xb0, v224
	v_ashrrev_i32_e32 v75, 31, v74
	v_lshlrev_b64 v[76:77], 12, v[74:75]
	v_lshl_add_u64 v[34:35], v[244:245], 0, v[76:77]
	global_load_dwordx4 v[46:49], v[34:35], off
	global_load_dwordx4 v[42:45], v[34:35], off offset:64
	global_load_dwordx4 v[38:41], v[34:35], off offset:512
	s_nop 0
	global_load_dwordx4 v[34:37], v[34:35], off offset:576
	v_readlane_b32 s4, v252, 3
	v_readlane_b32 s10, v252, 9
	v_readlane_b32 s11, v252, 10
	v_readlane_b32 s5, v252, 4
	s_and_b64 vcc, exec, s[54:55]
	s_cbranch_vccz .Leprv_5
	s_waitcnt vmcnt(8)
.Leprv_5:
	s_waitcnt vmcnt(16)
	v_pk_fma_f32 v[72:73], v[32:33], v[232:233], v[64:65]
	v_lshl_add_u64 v[66:67], s[10:11], 0, v[92:93]
	v_pk_fma_f32 v[70:71], v[30:31], v[234:235], v[62:63]
	v_lshl_add_u64 v[78:79], v[222:223], 2, v[66:67]
	s_mov_b64 s[4:5], -1
	s_and_b64 vcc, exec, s[54:55]
	s_waitcnt vmcnt(15)
	v_pk_fma_f32 v[66:67], v[26:27], v[236:237], v[58:59]
	s_waitcnt vmcnt(14)
	v_pk_fma_f32 v[62:63], v[22:23], v[238:239], v[54:55]
	s_waitcnt vmcnt(13)
	v_pk_fma_f32 v[30:31], v[18:19], v[240:241], v[50:51]
	v_readlane_b32 s6, v252, 5
	v_readlane_b32 s7, v252, 6
	v_readlane_b32 s8, v252, 7
	v_readlane_b32 s9, v252, 8
	global_store_dwordx4 v[78:79], v[70:73], off
	s_cbranch_vccz .LBB0_513
	v_pk_fma_f32 v[68:69], v[28:29], v[230:231], v[60:61]
	v_pk_fma_f32 v[64:65], v[24:25], v[228:229], v[56:57]
	v_pk_fma_f32 v[32:33], v[20:21], v[226:227], v[52:53]
	global_store_dwordx4 v[78:79], v[66:69], off offset:64
	global_store_dwordx4 v[78:79], v[62:65], off offset:512
	global_store_dwordx4 v[78:79], v[30:33], off offset:576
	s_mov_b64 s[4:5], 0

.LBB0_517:
	v_readlane_b32 s4, v252, 3
	v_readlane_b32 s10, v252, 9
	v_readlane_b32 s11, v252, 10
	v_readlane_b32 s5, v252, 4
	s_and_b64 vcc, exec, s[54:55]
	s_cbranch_vccz .Leprv_6
	s_waitcnt vmcnt(4)
.Leprv_6:
	s_waitcnt vmcnt(12)
	v_pk_fma_f32 v[28:29], v[16:17], v[232:233], v[48:49]
	v_lshl_add_u64 v[18:19], s[10:11], 0, v[76:77]
	v_pk_fma_f32 v[26:27], v[14:15], v[234:235], v[46:47]
	v_lshl_add_u64 v[30:31], v[222:223], 2, v[18:19]
	s_mov_b64 s[4:5], -1
	s_and_b64 vcc, exec, s[54:55]
	s_waitcnt vmcnt(11)
	v_pk_fma_f32 v[22:23], v[10:11], v[236:237], v[42:43]
	s_waitcnt vmcnt(10)
	v_pk_fma_f32 v[18:19], v[6:7], v[238:239], v[38:39]
	s_waitcnt vmcnt(9)
	v_pk_fma_f32 v[14:15], v[2:3], v[240:241], v[34:35]
	v_readlane_b32 s6, v252, 5
	v_readlane_b32 s7, v252, 6
	v_readlane_b32 s8, v252, 7
	v_readlane_b32 s9, v252, 8
	global_store_dwordx4 v[30:31], v[26:29], off
	s_cbranch_vccz .LBB0_519
	v_pk_fma_f32 v[24:25], v[12:13], v[230:231], v[44:45]
	v_pk_fma_f32 v[20:21], v[8:9], v[228:229], v[40:41]
	v_pk_fma_f32 v[16:17], v[4:5], v[226:227], v[36:37]
	global_store_dwordx4 v[30:31], v[22:25], off offset:64
	global_store_dwordx4 v[30:31], v[18:21], off offset:512
	global_store_dwordx4 v[30:31], v[14:17], off offset:576
	s_mov_b64 s[4:5], 0

.LBB0_621:
	s_andn2_b64 vcc, exec, s[4:5]
	s_cbranch_vccnz .LBB0_670
	v_readlane_b32 s4, v254, 37
	v_readlane_b32 s5, v254, 38
	s_cmp_lt_i32 s4, 6
	s_mov_b64 s[4:5], -1
	v_readlane_b32 s6, v254, 39
	v_readlane_b32 s7, v254, 40
	s_cbranch_scc1 .LBB0_647
	v_readlane_b32 s4, v254, 37
	s_cmp_eq_u32 s4, 6
	v_readlane_b32 s5, v254, 38
	v_readlane_b32 s6, v254, 39
	v_readlane_b32 s7, v254, 40
	s_cbranch_scc0 .LBB0_646
	s_mov_b64 s[22:23], s[64:65]
	s_mov_b32 s16, 0x3f000
	s_movk_i32 s2, 0xc00
	v_cmp_gt_i32_e32 vcc, s2, v63
	s_mov_b64 s[4:5], exec
	v_readlane_b32 s64, v253, 49
	v_readlane_b32 s70, v253, 55
	v_readlane_b32 s71, v253, 56
	s_and_b64 s[2:3], s[4:5], vcc
	v_readlane_b32 s66, v253, 51
	v_readlane_b32 s67, v253, 52
	v_readlane_b32 s68, v253, 53
	v_readlane_b32 s69, v253, 54
	s_mov_b32 s92, 0x48000
	s_mov_b32 s71, 0x12000
	s_mov_b32 s70, 0x9000
	v_readlane_b32 s18, v252, 20
	v_readlane_b32 s19, v252, 21
	s_mov_b32 s20, 0x10000
	s_mov_b32 s13, 0x24000
	s_mov_b32 s14, 0x2d000
	s_mov_b32 s15, 0x36000
	v_readlane_b32 s65, v253, 50
	v_readlane_b32 s72, v253, 57
	v_readlane_b32 s73, v253, 58
	v_readlane_b32 s74, v253, 59
	v_readlane_b32 s75, v253, 60
	v_readlane_b32 s76, v253, 61
	v_readlane_b32 s77, v253, 62
	v_readlane_b32 s78, v253, 63
	v_readlane_b32 s79, v254, 0
	s_mov_b64 exec, s[2:3]
	s_cbranch_execz .LBB0_631
	v_lshl_add_u32 v4, v63, 2, 0
	v_readlane_b32 s48, v253, 33
	v_readlane_b32 s49, v253, 34
	v_readlane_b32 s50, v253, 35
	v_readlane_b32 s51, v253, 36
	v_readlane_b32 s52, v253, 37
	v_readlane_b32 s53, v253, 38
	v_readlane_b32 s54, v253, 39
	v_readlane_b32 s55, v253, 40
	v_readlane_b32 s56, v253, 41
	v_readlane_b32 s57, v253, 42
	v_readlane_b32 s58, v253, 43
	v_readlane_b32 s59, v253, 44
	v_readlane_b32 s60, v253, 45
	v_readlane_b32 s61, v253, 46
	v_readlane_b32 s62, v253, 47
	v_readlane_b32 s63, v253, 48
	s_nop 4
	v_lshlrev_b32_e32 v175, 2, v63
	v_add_u32_e32 v176, 0x1000, v175
	global_load_dword v168, v175, s[62:63]
	global_load_dword v169, v175, s[62:63] offset:2048
	global_load_dword v170, v175, s[60:61]
	global_load_dword v171, v175, s[60:61] offset:2048
	global_load_dword v172, v176, s[60:61]
	global_load_dword v173, v176, s[60:61] offset:2048
	s_waitcnt vmcnt(0)
	v_mul_f32_e32 v2, 0xbfb8aa3b, v168
	v_exp_f32_e32 v2, v2
	s_nop 0
	v_add_f32_e32 v2, 1.0, v2
	v_div_scale_f32 v174, s[2:3], v2, v2, v168
	v_rcp_f32_e32 v6, v174
	v_div_scale_f32 v7, vcc, v168, v2, v168
	v_fma_f32 v8, -v174, v6, 1.0
	v_fmac_f32_e32 v6, v8, v6
	v_mul_f32_e32 v8, v7, v6
	v_fma_f32 v9, -v174, v8, v7
	v_fmac_f32_e32 v8, v9, v6
	v_fma_f32 v174, -v174, v8, v7
	v_div_fmas_f32 v174, v174, v6, v8
	v_div_fixup_f32 v168, v174, v2, v168
	ds_write_b32 v4, v168
	v_mul_f32_e32 v2, 0xbfb8aa3b, v169
	v_exp_f32_e32 v2, v2
	s_nop 0
	v_add_f32_e32 v2, 1.0, v2
	v_div_scale_f32 v174, s[2:3], v2, v2, v169
	v_rcp_f32_e32 v6, v174
	v_div_scale_f32 v7, vcc, v169, v2, v169
	v_fma_f32 v8, -v174, v6, 1.0
	v_fmac_f32_e32 v6, v8, v6
	v_mul_f32_e32 v8, v7, v6
	v_fma_f32 v9, -v174, v8, v7
	v_fmac_f32_e32 v8, v9, v6
	v_fma_f32 v174, -v174, v8, v7
	v_div_fmas_f32 v174, v174, v6, v8
	v_div_fixup_f32 v169, v174, v2, v169
	ds_write_b32 v4, v169 offset:2048
	v_mul_f32_e32 v2, 0xbfb8aa3b, v170
	v_exp_f32_e32 v2, v2
	s_nop 0
	v_add_f32_e32 v2, 1.0, v2
	v_div_scale_f32 v174, s[2:3], v2, v2, v170
	v_rcp_f32_e32 v6, v174
	v_div_scale_f32 v7, vcc, v170, v2, v170
	v_fma_f32 v8, -v174, v6, 1.0
	v_fmac_f32_e32 v6, v8, v6
	v_mul_f32_e32 v8, v7, v6
	v_fma_f32 v9, -v174, v8, v7
	v_fmac_f32_e32 v8, v9, v6
	v_fma_f32 v174, -v174, v8, v7
	v_div_fmas_f32 v174, v174, v6, v8
	v_div_fixup_f32 v170, v174, v2, v170
	ds_write_b32 v4, v170 offset:4096
	v_mul_f32_e32 v2, 0xbfb8aa3b, v171
	v_exp_f32_e32 v2, v2
	s_nop 0
	v_add_f32_e32 v2, 1.0, v2
	v_div_scale_f32 v174, s[2:3], v2, v2, v171
	v_rcp_f32_e32 v6, v174
	v_div_scale_f32 v7, vcc, v171, v2, v171
	v_fma_f32 v8, -v174, v6, 1.0
	v_fmac_f32_e32 v6, v8, v6
	v_mul_f32_e32 v8, v7, v6
	v_fma_f32 v9, -v174, v8, v7
	v_fmac_f32_e32 v8, v9, v6
	v_fma_f32 v174, -v174, v8, v7
	v_div_fmas_f32 v174, v174, v6, v8
	v_div_fixup_f32 v171, v174, v2, v171
	ds_write_b32 v4, v171 offset:6144
	v_mul_f32_e32 v2, 0xbfb8aa3b, v172
	v_exp_f32_e32 v2, v2
	s_nop 0
	v_add_f32_e32 v2, 1.0, v2
	v_div_scale_f32 v174, s[2:3], v2, v2, v172
	v_rcp_f32_e32 v6, v174
	v_div_scale_f32 v7, vcc, v172, v2, v172
	v_fma_f32 v8, -v174, v6, 1.0
	v_fmac_f32_e32 v6, v8, v6
	v_mul_f32_e32 v8, v7, v6
	v_fma_f32 v9, -v174, v8, v7
	v_fmac_f32_e32 v8, v9, v6
	v_fma_f32 v174, -v174, v8, v7
	v_div_fmas_f32 v174, v174, v6, v8
	v_div_fixup_f32 v172, v174, v2, v172
	ds_write_b32 v4, v172 offset:8192
	v_mul_f32_e32 v2, 0xbfb8aa3b, v173
	v_exp_f32_e32 v2, v2
	s_nop 0
	v_add_f32_e32 v2, 1.0, v2
	v_div_scale_f32 v174, s[2:3], v2, v2, v173
	v_rcp_f32_e32 v6, v174
	v_div_scale_f32 v7, vcc, v173, v2, v173
	v_fma_f32 v8, -v174, v6, 1.0
	v_fmac_f32_e32 v6, v8, v6
	v_mul_f32_e32 v8, v7, v6
	v_fma_f32 v9, -v174, v8, v7
	v_fmac_f32_e32 v8, v9, v6
	v_fma_f32 v174, -v174, v8, v7
	v_div_fmas_f32 v174, v174, v6, v8
	v_div_fixup_f32 v173, v174, v2, v173
	ds_write_b32 v4, v173 offset:10240

.LBB0_835:
	v_readlane_b32 s52, v253, 49
	s_and_b64 vcc, exec, s[4:5]
	v_readlane_b32 s54, v253, 51
	v_readlane_b32 s55, v253, 52
	v_readlane_b32 s56, v253, 53
	v_readlane_b32 s57, v253, 54
	v_readlane_b32 s58, v253, 55
	v_readlane_b32 s59, v253, 56
	v_readlane_b32 s60, v253, 57
	v_readlane_b32 s61, v253, 58
	v_readlane_b32 s62, v253, 59
	v_readlane_b32 s63, v253, 60
	v_readlane_b32 s64, v253, 61
	v_readlane_b32 s65, v253, 62
	v_readlane_b32 s66, v253, 63
	v_readlane_b32 s67, v254, 0
	v_readlane_b32 s53, v253, 50
	s_cbranch_vccz .LBB0_946
	s_movk_i32 s0, 0xc00
	v_cmp_gt_i32_e32 vcc, s0, v205
	s_and_saveexec_b64 s[0:1], vcc
	v_readlane_b32 s14, v254, 46
	s_movk_i32 s10, 0xfc00
	s_movk_i32 s11, 0x3ff
	s_movk_i32 s12, 0x9ff
	v_readlane_b32 s15, v254, 47
	s_cbranch_execz .LBB0_843
	v_readlane_b32 s2, v254, 41
	s_lshl_b32 s2, s2, 8
	s_add_i32 s2, s2, 0
	v_lshl_add_u32 v4, v206, 2, s2
	v_lshlrev_b32_e32 v175, 2, v205
	v_add_u32_e32 v176, 0x1000, v175
	global_load_dword v168, v175, s[50:51]
	global_load_dword v169, v175, s[50:51] offset:2048
	global_load_dword v170, v175, s[48:49]
	global_load_dword v171, v175, s[48:49] offset:2048
	global_load_dword v172, v176, s[48:49]
	global_load_dword v173, v176, s[48:49] offset:2048
	s_waitcnt vmcnt(0)
	v_mul_f32_e32 v2, 0xbfb8aa3b, v168
	v_exp_f32_e32 v2, v2
	s_nop 0
	v_add_f32_e32 v2, 1.0, v2
	v_div_scale_f32 v174, s[2:3], v2, v2, v168
	v_rcp_f32_e32 v6, v174
	v_div_scale_f32 v7, vcc, v168, v2, v168
	v_fma_f32 v8, -v174, v6, 1.0
	v_fmac_f32_e32 v6, v8, v6
	v_mul_f32_e32 v8, v7, v6
	v_fma_f32 v9, -v174, v8, v7
	v_fmac_f32_e32 v8, v9, v6
	v_fma_f32 v174, -v174, v8, v7
	v_div_fmas_f32 v174, v174, v6, v8
	v_div_fixup_f32 v168, v174, v2, v168
	ds_write_b32 v4, v168
	v_mul_f32_e32 v2, 0xbfb8aa3b, v169
	v_exp_f32_e32 v2, v2
	s_nop 0
	v_add_f32_e32 v2, 1.0, v2
	v_div_scale_f32 v174, s[2:3], v2, v2, v169
	v_rcp_f32_e32 v6, v174
	v_div_scale_f32 v7, vcc, v169, v2, v169
	v_fma_f32 v8, -v174, v6, 1.0
	v_fmac_f32_e32 v6, v8, v6
	v_mul_f32_e32 v8, v7, v6
	v_fma_f32 v9, -v174, v8, v7
	v_fmac_f32_e32 v8, v9, v6
	v_fma_f32 v174, -v174, v8, v7
	v_div_fmas_f32 v174, v174, v6, v8
	v_div_fixup_f32 v169, v174, v2, v169
	ds_write_b32 v4, v169 offset:2048
	v_mul_f32_e32 v2, 0xbfb8aa3b, v170
	v_exp_f32_e32 v2, v2
	s_nop 0
	v_add_f32_e32 v2, 1.0, v2
	v_div_scale_f32 v174, s[2:3], v2, v2, v170
	v_rcp_f32_e32 v6, v174
	v_div_scale_f32 v7, vcc, v170, v2, v170
	v_fma_f32 v8, -v174, v6, 1.0
	v_fmac_f32_e32 v6, v8, v6
	v_mul_f32_e32 v8, v7, v6
	v_fma_f32 v9, -v174, v8, v7
	v_fmac_f32_e32 v8, v9, v6
	v_fma_f32 v174, -v174, v8, v7
	v_div_fmas_f32 v174, v174, v6, v8
	v_div_fixup_f32 v170, v174, v2, v170
	ds_write_b32 v4, v170 offset:4096
	v_mul_f32_e32 v2, 0xbfb8aa3b, v171
	v_exp_f32_e32 v2, v2
	s_nop 0
	v_add_f32_e32 v2, 1.0, v2
	v_div_scale_f32 v174, s[2:3], v2, v2, v171
	v_rcp_f32_e32 v6, v174
	v_div_scale_f32 v7, vcc, v171, v2, v171
	v_fma_f32 v8, -v174, v6, 1.0
	v_fmac_f32_e32 v6, v8, v6
	v_mul_f32_e32 v8, v7, v6
	v_fma_f32 v9, -v174, v8, v7
	v_fmac_f32_e32 v8, v9, v6
	v_fma_f32 v174, -v174, v8, v7
	v_div_fmas_f32 v174, v174, v6, v8
	v_div_fixup_f32 v171, v174, v2, v171
	ds_write_b32 v4, v171 offset:6144
	v_mul_f32_e32 v2, 0xbfb8aa3b, v172
	v_exp_f32_e32 v2, v2
	s_nop 0
	v_add_f32_e32 v2, 1.0, v2
	v_div_scale_f32 v174, s[2:3], v2, v2, v172
	v_rcp_f32_e32 v6, v174
	v_div_scale_f32 v7, vcc, v172, v2, v172
	v_fma_f32 v8, -v174, v6, 1.0
	v_fmac_f32_e32 v6, v8, v6
	v_mul_f32_e32 v8, v7, v6
	v_fma_f32 v9, -v174, v8, v7
	v_fmac_f32_e32 v8, v9, v6
	v_fma_f32 v174, -v174, v8, v7
	v_div_fmas_f32 v174, v174, v6, v8
	v_div_fixup_f32 v172, v174, v2, v172
	ds_write_b32 v4, v172 offset:8192
	v_mul_f32_e32 v2, 0xbfb8aa3b, v173
	v_exp_f32_e32 v2, v2
	s_nop 0
	v_add_f32_e32 v2, 1.0, v2
	v_div_scale_f32 v174, s[2:3], v2, v2, v173
	v_rcp_f32_e32 v6, v174
	v_div_scale_f32 v7, vcc, v173, v2, v173
	v_fma_f32 v8, -v174, v6, 1.0
	v_fmac_f32_e32 v6, v8, v6
	v_mul_f32_e32 v8, v7, v6
	v_fma_f32 v9, -v174, v8, v7
	v_fmac_f32_e32 v8, v9, v6
	v_fma_f32 v174, -v174, v8, v7
	v_div_fmas_f32 v174, v174, v6, v8
	v_div_fixup_f32 v173, v174, v2, v173
	ds_write_b32 v4, v173 offset:10240
